# P0 weight re-layout rewritten as one shared compact item body (15 inlined copies removed)
# baseline (speedup 1.0000x reference)
; #define SEG_GU(Wsrc, gainp, dst, half) if (r < I_GU) { const int nblk = FF / 64, kb = r / nblk, nb = r % nblk, n0 = 64 * nb; \
;                 p0_item(Wsrc, FF, n0, 64 * kb, gainp, dst, DM, (n0 / 128) * 256 + (n0 % 128) + (half) * 128, scr, lane); continue; } r -= I_GU;
; #define SEG_ID(Wsrc, ldw, colbase, Kdim, ncols, gainp, dst, drow, cnt) if (r < (cnt)) { const int nblk = (ncols) / 64, kb = r / nblk, nb = r % nblk; \
;                 p0_item(Wsrc, ldw, (colbase) + 64 * nb, 64 * kb, gainp, dst, Kdim, (drow) + 64 * nb, scr, lane); continue; } r -= (cnt);
; __global__ void __launch_bounds__(NWAVES * 64, 2) fwd_megakernel(Args args) {
;     ...
;         for (int it = gw; it < NITEMS; it += NGW) {
;             int r = it;
;     ...
;             SEG_GU(args.in[3], args.in[2], W1, 0)
;             SEG_GU(args.in[4], args.in[2], W1, 1)
;             SEG_ID(args.in[5], DM, 0, FF, DM, (const float*)nullptr, WD1, 0, I_DN)
;             SEG_ID(args.in[7], DIN, 0, DM, 1024, args.in[6], WQK, 0, I_IN)
;             SEG_ID(args.in[7], DIN, 1024, DM, 1024, args.in[6], WQK, 1024, I_IN)
;             SEG_ID(args.in[7], DIN, 2048, DM, 1024, args.in[6], WV, 0, I_IN)
;             SEG_ID(args.in[7], DIN, 3080, DM, 1024, args.in[6], WQK, 2048, I_IN)
;             SEG_ID(args.in[7], DIN, 4104, DM, 1024, args.in[6], WQK, 3072, I_IN)
;             SEG_ID(args.in[7], DIN, 5128, DM, 1024, args.in[6], WV, 1024, I_IN)
;             SEG_ID(args.in[9], DM, 0, DM, DM, (const float*)nullptr, WO, 0, I_SQ)
;             SEG_GU(args.in[11], args.in[10], W2, 0)
;             SEG_GU(args.in[12], args.in[10], W2, 1)
;             SEG_ID(args.in[13], DM, 0, FF, DM, (const float*)nullptr, WD2, 0, I_DN)
;             SEG_ID(args.in[15], DM, 0, DM, DM, args.in[14], WPG, 0, I_SQ)
;             SEG_ID(args.in[16], DM, 0, PLE, DM, (const float*)nullptr, WPP, 0, I_PP)
.LBB0_28:
	v_writelane_b32 v250, s30, 30
	s_nop 1
	v_writelane_b32 v250, s31, 31
	v_writelane_b32 v250, s27, 32
	s_or_b64 exec, exec, s[4:5]
	s_lshr_b32 s64, s3, 6
	s_lshl_b32 s1, s26, 3
	s_add_i32 s1, s1, s64
	s_add_u32 s4, s60, 0x200000
	s_addc_u32 s5, s61, 0
	v_writelane_b32 v250, s4, 34
	v_and_b32_e32 v168, 63, v166
	s_nop 0
	v_writelane_b32 v250, s5, 35
	s_add_u32 s4, s60, 0x2e00000
	s_addc_u32 s5, s61, 0
	v_writelane_b32 v250, s4, 36
	s_nop 1
	v_writelane_b32 v250, s5, 37
	s_add_u32 s4, s60, 0x4400000
	s_addc_u32 s5, s61, 0
	v_writelane_b32 v250, s4, 38
	s_nop 1
	v_writelane_b32 v250, s5, 39
	s_add_u32 s4, s60, 0x5400000
	s_addc_u32 s5, s61, 0
	v_writelane_b32 v250, s4, 40
	s_nop 1
	v_writelane_b32 v250, s5, 41
	s_add_u32 s4, s60, 0x5c00000
	s_addc_u32 s5, s61, 0
	v_writelane_b32 v250, s4, 42
	s_nop 1
	v_writelane_b32 v250, s5, 43
	s_add_u32 s4, s60, 0x6400000
	s_addc_u32 s5, s61, 0
	v_writelane_b32 v250, s4, 44
	s_nop 1
	v_writelane_b32 v250, s5, 45
	s_add_u32 s4, s60, 0x9000000
	s_addc_u32 s5, s61, 0
	v_writelane_b32 v250, s4, 46
	s_nop 1
	v_writelane_b32 v250, s5, 47
	s_add_u32 s4, s60, 0xa600000
	s_addc_u32 s5, s61, 0
	v_writelane_b32 v250, s4, 48
	s_nop 1
	v_writelane_b32 v250, s5, 49
	s_add_u32 s4, s60, 0xae00000
	s_addc_u32 s5, s61, 0
	v_writelane_b32 v250, s4, 50
	s_cmpk_gt_i32 s1, 0x567f
	s_nop 0
	v_writelane_b32 v250, s5, 51
	v_writelane_b32 v250, s1, 52
	s_cbranch_scc1 .LBB0_120
	v_lshlrev_b32_e32 v66, 2, v168
	v_and_b32_e32 v0, 7, v168
	v_lshlrev_b32_e32 v67, 5, v0
	v_lshrrev_b32_e32 v79, 3, v168
	s_mul_i32 s3, s64, 0x4100
	v_add_u32_e32 v76, s3, v66
	v_mul_u32_u24_e32 v77, 0x820, v0
	v_lshl_add_u32 v77, v79, 2, v77
	v_add_u32_e32 v77, s3, v77
	v_lshlrev_b32_e32 v92, 4, v0
	v_readlane_b32 s55, v250, 52
	s_lshl_b32 s1, s62, 3
.Lp0_loop:
	s_mov_b32 s3, s55
	s_cmpk_lt_u32 s3, 0xb00
	s_cbranch_scc1 .Lp0_seg0
	s_sub_u32 s3, s3, 0xb00
	s_cmpk_lt_u32 s3, 0xb00
	s_cbranch_scc1 .Lp0_seg1
	s_sub_u32 s3, s3, 0xb00
	s_cmpk_lt_u32 s3, 0xb00
	s_cbranch_scc1 .Lp0_seg2
	s_sub_u32 s3, s3, 0xb00
	s_cmpk_lt_u32 s3, 0x200
	s_cbranch_scc1 .Lp0_seg3
	s_sub_u32 s3, s3, 0x200
	s_cmpk_lt_u32 s3, 0x200
	s_cbranch_scc1 .Lp0_seg4
	s_sub_u32 s3, s3, 0x200
	s_cmpk_lt_u32 s3, 0x200
	s_cbranch_scc1 .Lp0_seg5
	s_sub_u32 s3, s3, 0x200
	s_cmpk_lt_u32 s3, 0x200
	s_cbranch_scc1 .Lp0_seg6
	s_sub_u32 s3, s3, 0x200
	s_cmpk_lt_u32 s3, 0x200
	s_cbranch_scc1 .Lp0_seg7
	s_sub_u32 s3, s3, 0x200
	s_cmpk_lt_u32 s3, 0x200
	s_cbranch_scc1 .Lp0_seg8
	s_sub_u32 s3, s3, 0x200
	s_cmpk_lt_u32 s3, 0x400
	s_cbranch_scc1 .Lp0_seg9
	s_sub_u32 s3, s3, 0x400
	s_cmpk_lt_u32 s3, 0xb00
	s_cbranch_scc1 .Lp0_seg10
	s_sub_u32 s3, s3, 0xb00
	s_cmpk_lt_u32 s3, 0xb00
	s_cbranch_scc1 .Lp0_seg11
	s_sub_u32 s3, s3, 0xb00
	s_cmpk_lt_u32 s3, 0xb00
	s_cbranch_scc1 .Lp0_seg12
	s_sub_u32 s3, s3, 0xb00
	s_cmpk_lt_u32 s3, 0x400
	s_cbranch_scc1 .Lp0_seg13
	s_sub_u32 s3, s3, 0x400
	s_branch .Lp0_seg14
.Lp0_seg0:
	s_mov_b64 s[28:29], s[14:15]
	s_mov_b64 s[34:35], s[12:13]
	s_add_u32 s36, s60, 0x200000
	s_addc_u32 s37, s61, 0
	s_mul_i32 s4, s3, 0xba3
	s_lshr_b32 s4, s4, 18
	s_mul_i32 s5, s4, 88
	s_sub_u32 s5, s3, s5
	s_lshl_b32 s33, s4, 6
	s_lshl_b32 s31, s5, 6
	s_movk_i32 s30, 0x1600
	s_movk_i32 s38, 0x800
	s_lshr_b32 s6, s5, 1
	s_lshl_b32 s6, s6, 8
	s_and_b32 s7, s5, 1
	s_lshl_b32 s7, s7, 6
	s_add_u32 s39, s6, s7
	s_branch .Lp0_item
.Lp0_seg1:
	s_mov_b64 s[28:29], s[16:17]
	s_mov_b64 s[34:35], s[12:13]
	s_add_u32 s36, s60, 0x200000
	s_addc_u32 s37, s61, 0
	s_mul_i32 s4, s3, 0xba3
	s_lshr_b32 s4, s4, 18
	s_mul_i32 s5, s4, 88
	s_sub_u32 s5, s3, s5
	s_lshl_b32 s33, s4, 6
	s_lshl_b32 s31, s5, 6
	s_movk_i32 s30, 0x1600
	s_movk_i32 s38, 0x800
	s_lshr_b32 s6, s5, 1
	s_lshl_b32 s6, s6, 8
	s_and_b32 s7, s5, 1
	s_lshl_b32 s7, s7, 6
	s_add_u32 s39, s6, s7
	s_add_u32 s39, s39, 0x80
	s_branch .Lp0_item
.Lp0_seg2:
	s_mov_b64 s[28:29], s[18:19]
	s_mov_b64 s[34:35], 0
	s_add_u32 s36, s60, 0x2e00000
	s_addc_u32 s37, s61, 0
	s_lshr_b32 s4, s3, 5
	s_and_b32 s5, s3, 31
	s_lshl_b32 s33, s4, 6
	s_lshl_b32 s5, s5, 6
	s_mov_b32 s31, s5
	s_movk_i32 s30, 0x800
	s_movk_i32 s38, 0x1600
	s_mov_b32 s39, s5
	s_branch .Lp0_item
.Lp0_seg3:
	s_mov_b64 s[28:29], s[22:23]
	s_mov_b64 s[34:35], s[20:21]
	s_add_u32 s36, s60, 0x4400000
	s_addc_u32 s37, s61, 0
	s_lshr_b32 s4, s3, 4
	s_and_b32 s5, s3, 15
	s_lshl_b32 s33, s4, 6
	s_lshl_b32 s5, s5, 6
	s_mov_b32 s31, s5
	s_movk_i32 s30, 0x1808
	s_movk_i32 s38, 0x800
	s_mov_b32 s39, s5
	s_branch .Lp0_item
.Lp0_seg4:
	s_mov_b64 s[28:29], s[22:23]
	s_mov_b64 s[34:35], s[20:21]
	s_add_u32 s36, s60, 0x4400000
	s_addc_u32 s37, s61, 0
	s_lshr_b32 s4, s3, 4
	s_and_b32 s5, s3, 15
	s_lshl_b32 s33, s4, 6
	s_lshl_b32 s5, s5, 6
	s_add_u32 s31, s5, 0x400
	s_movk_i32 s30, 0x1808
	s_movk_i32 s38, 0x800
	s_add_u32 s39, s5, 0x400
	s_branch .Lp0_item
.Lp0_seg5:
	s_mov_b64 s[28:29], s[22:23]
	s_mov_b64 s[34:35], s[20:21]
	s_add_u32 s36, s60, 0x5400000
	s_addc_u32 s37, s61, 0
	s_lshr_b32 s4, s3, 4
	s_and_b32 s5, s3, 15
	s_lshl_b32 s33, s4, 6
	s_lshl_b32 s5, s5, 6
	s_add_u32 s31, s5, 0x800
	s_movk_i32 s30, 0x1808
	s_movk_i32 s38, 0x800
	s_mov_b32 s39, s5
	s_branch .Lp0_item
.Lp0_seg6:
	s_mov_b64 s[28:29], s[22:23]
	s_mov_b64 s[34:35], s[20:21]
	s_add_u32 s36, s60, 0x4400000
	s_addc_u32 s37, s61, 0
	s_lshr_b32 s4, s3, 4
	s_and_b32 s5, s3, 15
	s_lshl_b32 s33, s4, 6
	s_lshl_b32 s5, s5, 6
	s_add_u32 s31, s5, 0xc08
	s_movk_i32 s30, 0x1808
	s_movk_i32 s38, 0x800
	s_add_u32 s39, s5, 0x800
	s_branch .Lp0_item
.Lp0_seg7:
	s_mov_b64 s[28:29], s[22:23]
	s_mov_b64 s[34:35], s[20:21]
	s_add_u32 s36, s60, 0x4400000
	s_addc_u32 s37, s61, 0
	s_lshr_b32 s4, s3, 4
	s_and_b32 s5, s3, 15
	s_lshl_b32 s33, s4, 6
	s_lshl_b32 s5, s5, 6
	s_add_u32 s31, s5, 0x1008
	s_movk_i32 s30, 0x1808
	s_movk_i32 s38, 0x800
	s_add_u32 s39, s5, 0xc00
	s_branch .Lp0_item
; #define LAS __attribute__((address_space(3)))
; #define SEG_GU(Wsrc, gainp, dst, half) if (r < I_GU) { const int nblk = FF / 64, kb = r / nblk, nb = r % nblk, n0 = 64 * nb; \
;                 p0_item(Wsrc, FF, n0, 64 * kb, gainp, dst, DM, (n0 / 128) * 256 + (n0 % 128) + (half) * 128, scr, lane); continue; } r -= I_GU;
; #define SEG_ID(Wsrc, ldw, colbase, Kdim, ncols, gainp, dst, drow, cnt) if (r < (cnt)) { const int nblk = (ncols) / 64, kb = r / nblk, nb = r % nblk; \
;                 p0_item(Wsrc, ldw, (colbase) + 64 * nb, 64 * kb, gainp, dst, Kdim, (drow) + 64 * nb, scr, lane); continue; } r -= (cnt);
; __device__ __forceinline__ void p0_item(const float* W, int ldw, int col0, int k0, const float* gain, bf16_t* WT, int K, int drow0, LAS float* scr, int lane) {
;     float v[64];
;     const float* src = W + (size_t)k0 * ldw + col0 + lane;
; #pragma unroll
;     for (int i = 0; i < 64; ++i) v[i] = src[(size_t)i * ldw];
; __global__ void __launch_bounds__(NWAVES * 64, 2) fwd_megakernel(Args args) {
;     ...
;             SEG_GU(args.in[11], args.in[10], W2, 0)
;             SEG_GU(args.in[12], args.in[10], W2, 1)
;             SEG_ID(args.in[13], DM, 0, FF, DM, (const float*)nullptr, WD2, 0, I_DN)
;             SEG_ID(args.in[15], DM, 0, DM, DM, args.in[14], WPG, 0, I_SQ)
;             SEG_ID(args.in[16], DM, 0, PLE, DM, (const float*)nullptr, WPP, 0, I_PP)
.Lp0_seg8:
	s_mov_b64 s[28:29], s[22:23]
	s_mov_b64 s[34:35], s[20:21]
	s_add_u32 s36, s60, 0x5400000
	s_addc_u32 s37, s61, 0
	s_lshr_b32 s4, s3, 4
	s_and_b32 s5, s3, 15
	s_lshl_b32 s33, s4, 6
	s_lshl_b32 s5, s5, 6
	s_add_u32 s31, s5, 0x1408
	s_movk_i32 s30, 0x1808
	s_movk_i32 s38, 0x800
	s_add_u32 s39, s5, 0x400
	s_branch .Lp0_item
.Lp0_seg9:
	v_readlane_b32 s28, v250, 14
	v_readlane_b32 s29, v250, 15
	s_mov_b64 s[34:35], 0
	s_add_u32 s36, s60, 0x5c00000
	s_addc_u32 s37, s61, 0
	s_lshr_b32 s4, s3, 5
	s_and_b32 s5, s3, 31
	s_lshl_b32 s33, s4, 6
	s_lshl_b32 s5, s5, 6
	s_mov_b32 s31, s5
	s_movk_i32 s30, 0x800
	s_movk_i32 s38, 0x800
	s_mov_b32 s39, s5
	s_branch .Lp0_item
.Lp0_seg10:
	v_readlane_b32 s28, v250, 18
	v_readlane_b32 s29, v250, 19
	v_readlane_b32 s34, v250, 16
	v_readlane_b32 s35, v250, 17
	s_add_u32 s36, s60, 0x6400000
	s_addc_u32 s37, s61, 0
	s_mul_i32 s4, s3, 0xba3
	s_lshr_b32 s4, s4, 18
	s_mul_i32 s5, s4, 88
	s_sub_u32 s5, s3, s5
	s_lshl_b32 s33, s4, 6
	s_lshl_b32 s31, s5, 6
	s_movk_i32 s30, 0x1600
	s_movk_i32 s38, 0x800
	s_lshr_b32 s6, s5, 1
	s_lshl_b32 s6, s6, 8
	s_and_b32 s7, s5, 1
	s_lshl_b32 s7, s7, 6
	s_add_u32 s39, s6, s7
	s_branch .Lp0_item
.Lp0_seg11:
	v_readlane_b32 s28, v250, 20
	v_readlane_b32 s29, v250, 21
	v_readlane_b32 s34, v250, 16
	v_readlane_b32 s35, v250, 17
	s_add_u32 s36, s60, 0x6400000
	s_addc_u32 s37, s61, 0
	s_mul_i32 s4, s3, 0xba3
	s_lshr_b32 s4, s4, 18
	s_mul_i32 s5, s4, 88
	s_sub_u32 s5, s3, s5
	s_lshl_b32 s33, s4, 6
	s_lshl_b32 s31, s5, 6
	s_movk_i32 s30, 0x1600
	s_movk_i32 s38, 0x800
	s_lshr_b32 s6, s5, 1
	s_lshl_b32 s6, s6, 8
	s_and_b32 s7, s5, 1
	s_lshl_b32 s7, s7, 6
	s_add_u32 s39, s6, s7
	s_add_u32 s39, s39, 0x80
	s_branch .Lp0_item
.Lp0_seg12:
	v_readlane_b32 s28, v250, 22
	v_readlane_b32 s29, v250, 23
	s_mov_b64 s[34:35], 0
	s_add_u32 s36, s60, 0x9000000
	s_addc_u32 s37, s61, 0
	s_lshr_b32 s4, s3, 5
	s_and_b32 s5, s3, 31
	s_lshl_b32 s33, s4, 6
	s_lshl_b32 s5, s5, 6
	s_mov_b32 s31, s5
	s_movk_i32 s30, 0x800
	s_movk_i32 s38, 0x1600
	s_mov_b32 s39, s5
	s_branch .Lp0_item
.Lp0_seg13:
	v_readlane_b32 s28, v250, 26
	v_readlane_b32 s29, v250, 27
	v_readlane_b32 s34, v250, 24
	v_readlane_b32 s35, v250, 25
	s_add_u32 s36, s60, 0xa600000
	s_addc_u32 s37, s61, 0
	s_lshr_b32 s4, s3, 5
	s_and_b32 s5, s3, 31
	s_lshl_b32 s33, s4, 6
	s_lshl_b32 s5, s5, 6
	s_mov_b32 s31, s5
	s_movk_i32 s30, 0x800
	s_movk_i32 s38, 0x800
	s_mov_b32 s39, s5
	s_branch .Lp0_item
.Lp0_seg14:
	v_readlane_b32 s28, v250, 0
	v_readlane_b32 s29, v250, 1
	s_mov_b64 s[34:35], 0
	s_add_u32 s36, s60, 0xae00000
	s_addc_u32 s37, s61, 0
	s_lshr_b32 s4, s3, 5
	s_and_b32 s5, s3, 31
	s_lshl_b32 s33, s4, 6
	s_lshl_b32 s5, s5, 6
	s_mov_b32 s31, s5
	s_movk_i32 s30, 0x800
	s_movk_i32 s38, 0x100
	s_mov_b32 s39, s5
	s_branch .Lp0_item
.Lp0_item:
	s_cmp_eq_u64 s[34:35], 0
	s_cbranch_scc1 .Lp0_nogain
	s_lshl_b32 s4, s33, 2
	s_add_u32 s42, s34, s4
	s_addc_u32 s43, s35, 0
	global_load_dwordx4 v[68:71], v67, s[42:43]
	global_load_dwordx4 v[72:75], v67, s[42:43] offset:16
	s_branch .Lp0_rows
.Lp0_nogain:
	v_mov_b32_e32 v68, 1.0
	v_mov_b32_e32 v69, 1.0
	v_mov_b32_e32 v70, 1.0
	v_mov_b32_e32 v71, 1.0
	v_mov_b32_e32 v72, 1.0
	v_mov_b32_e32 v73, 1.0
	v_mov_b32_e32 v74, 1.0
	v_mov_b32_e32 v75, 1.0
.Lp0_rows:
	s_mul_i32 s4, s33, s30
	s_add_u32 s4, s4, s31
	s_lshl_b32 s4, s4, 2
	s_add_u32 s40, s28, s4
	s_addc_u32 s41, s29, 0
	s_lshl_b32 s5, s30, 2
	global_load_dword v2, v66, s[40:41]
	s_add_u32 s40, s40, s5
	s_addc_u32 s41, s41, 0
	global_load_dword v3, v66, s[40:41]
	s_add_u32 s40, s40, s5
	s_addc_u32 s41, s41, 0
	global_load_dword v4, v66, s[40:41]
	s_add_u32 s40, s40, s5
	s_addc_u32 s41, s41, 0
	global_load_dword v5, v66, s[40:41]
	s_add_u32 s40, s40, s5
	s_addc_u32 s41, s41, 0
	global_load_dword v6, v66, s[40:41]
	s_add_u32 s40, s40, s5
	s_addc_u32 s41, s41, 0
	global_load_dword v7, v66, s[40:41]
	s_add_u32 s40, s40, s5
	s_addc_u32 s41, s41, 0
	global_load_dword v8, v66, s[40:41]
	s_add_u32 s40, s40, s5
	s_addc_u32 s41, s41, 0
	global_load_dword v9, v66, s[40:41]
	s_add_u32 s40, s40, s5
	s_addc_u32 s41, s41, 0
	global_load_dword v10, v66, s[40:41]
	s_add_u32 s40, s40, s5
	s_addc_u32 s41, s41, 0
	global_load_dword v11, v66, s[40:41]
	s_add_u32 s40, s40, s5
	s_addc_u32 s41, s41, 0
	global_load_dword v12, v66, s[40:41]
	s_add_u32 s40, s40, s5
	s_addc_u32 s41, s41, 0
	global_load_dword v13, v66, s[40:41]
	s_add_u32 s40, s40, s5
	s_addc_u32 s41, s41, 0
	global_load_dword v14, v66, s[40:41]
	s_add_u32 s40, s40, s5
	s_addc_u32 s41, s41, 0
	global_load_dword v15, v66, s[40:41]
	s_add_u32 s40, s40, s5
	s_addc_u32 s41, s41, 0
	global_load_dword v16, v66, s[40:41]
	s_add_u32 s40, s40, s5
	s_addc_u32 s41, s41, 0
	global_load_dword v17, v66, s[40:41]
	s_add_u32 s40, s40, s5
	s_addc_u32 s41, s41, 0
	global_load_dword v18, v66, s[40:41]
	s_add_u32 s40, s40, s5
	s_addc_u32 s41, s41, 0
	global_load_dword v19, v66, s[40:41]
	s_add_u32 s40, s40, s5
	s_addc_u32 s41, s41, 0
	global_load_dword v20, v66, s[40:41]
	s_add_u32 s40, s40, s5
	s_addc_u32 s41, s41, 0
	global_load_dword v21, v66, s[40:41]
	s_add_u32 s40, s40, s5
	s_addc_u32 s41, s41, 0
	global_load_dword v22, v66, s[40:41]
	s_add_u32 s40, s40, s5
	s_addc_u32 s41, s41, 0
	global_load_dword v23, v66, s[40:41]
	s_add_u32 s40, s40, s5
	s_addc_u32 s41, s41, 0
	global_load_dword v24, v66, s[40:41]
	s_add_u32 s40, s40, s5
	s_addc_u32 s41, s41, 0
	global_load_dword v25, v66, s[40:41]
	s_add_u32 s40, s40, s5
	s_addc_u32 s41, s41, 0
	global_load_dword v26, v66, s[40:41]
	s_add_u32 s40, s40, s5
	s_addc_u32 s41, s41, 0
	global_load_dword v27, v66, s[40:41]
	s_add_u32 s40, s40, s5
	s_addc_u32 s41, s41, 0
	global_load_dword v28, v66, s[40:41]
; __device__ __forceinline__ void p0_item(const float* W, int ldw, int col0, int k0, const float* gain, bf16_t* WT, int K, int drow0, LAS float* scr, int lane) {
;     ...
;     for (int i = 0; i < 64; ++i) v[i] = src[(size_t)i * ldw];
;     const int c = lane & 7;
;     f32x4 g0 = {1.f, 1.f, 1.f, 1.f}, g1 = {1.f, 1.f, 1.f, 1.f};
;     if (gain) { g0 = *(const f32x4*)(gain + k0 + 8 * c); g1 = *(const f32x4*)(gain + k0 + 8 * c + 4); }
; #pragma unroll
;     for (int i = 0; i < 64; ++i) scr[i * 65 + lane] = v[i];
	s_add_u32 s40, s40, s5
	s_addc_u32 s41, s41, 0
	global_load_dword v29, v66, s[40:41]
	s_add_u32 s40, s40, s5
	s_addc_u32 s41, s41, 0
	global_load_dword v30, v66, s[40:41]
	s_add_u32 s40, s40, s5
	s_addc_u32 s41, s41, 0
	global_load_dword v31, v66, s[40:41]
	s_add_u32 s40, s40, s5
	s_addc_u32 s41, s41, 0
	global_load_dword v32, v66, s[40:41]
	s_add_u32 s40, s40, s5
	s_addc_u32 s41, s41, 0
	global_load_dword v33, v66, s[40:41]
	s_add_u32 s40, s40, s5
	s_addc_u32 s41, s41, 0
	global_load_dword v34, v66, s[40:41]
	s_add_u32 s40, s40, s5
	s_addc_u32 s41, s41, 0
	global_load_dword v35, v66, s[40:41]
	s_add_u32 s40, s40, s5
	s_addc_u32 s41, s41, 0
	global_load_dword v36, v66, s[40:41]
	s_add_u32 s40, s40, s5
	s_addc_u32 s41, s41, 0
	global_load_dword v37, v66, s[40:41]
	s_add_u32 s40, s40, s5
	s_addc_u32 s41, s41, 0
	global_load_dword v38, v66, s[40:41]
	s_add_u32 s40, s40, s5
	s_addc_u32 s41, s41, 0
	global_load_dword v39, v66, s[40:41]
	s_add_u32 s40, s40, s5
	s_addc_u32 s41, s41, 0
	global_load_dword v40, v66, s[40:41]
	s_add_u32 s40, s40, s5
	s_addc_u32 s41, s41, 0
	global_load_dword v41, v66, s[40:41]
	s_add_u32 s40, s40, s5
	s_addc_u32 s41, s41, 0
	global_load_dword v42, v66, s[40:41]
	s_add_u32 s40, s40, s5
	s_addc_u32 s41, s41, 0
	global_load_dword v43, v66, s[40:41]
	s_add_u32 s40, s40, s5
	s_addc_u32 s41, s41, 0
	global_load_dword v44, v66, s[40:41]
	s_add_u32 s40, s40, s5
	s_addc_u32 s41, s41, 0
	global_load_dword v45, v66, s[40:41]
	s_add_u32 s40, s40, s5
	s_addc_u32 s41, s41, 0
	global_load_dword v46, v66, s[40:41]
	s_add_u32 s40, s40, s5
	s_addc_u32 s41, s41, 0
	global_load_dword v47, v66, s[40:41]
	s_add_u32 s40, s40, s5
	s_addc_u32 s41, s41, 0
	global_load_dword v48, v66, s[40:41]
	s_add_u32 s40, s40, s5
	s_addc_u32 s41, s41, 0
	global_load_dword v49, v66, s[40:41]
	s_add_u32 s40, s40, s5
	s_addc_u32 s41, s41, 0
	global_load_dword v50, v66, s[40:41]
	s_add_u32 s40, s40, s5
	s_addc_u32 s41, s41, 0
	global_load_dword v51, v66, s[40:41]
	s_add_u32 s40, s40, s5
	s_addc_u32 s41, s41, 0
	global_load_dword v52, v66, s[40:41]
	s_add_u32 s40, s40, s5
	s_addc_u32 s41, s41, 0
	global_load_dword v53, v66, s[40:41]
	s_add_u32 s40, s40, s5
	s_addc_u32 s41, s41, 0
	global_load_dword v54, v66, s[40:41]
	s_add_u32 s40, s40, s5
	s_addc_u32 s41, s41, 0
	global_load_dword v55, v66, s[40:41]
	s_add_u32 s40, s40, s5
	s_addc_u32 s41, s41, 0
	global_load_dword v56, v66, s[40:41]
	s_add_u32 s40, s40, s5
	s_addc_u32 s41, s41, 0
	global_load_dword v57, v66, s[40:41]
	s_add_u32 s40, s40, s5
	s_addc_u32 s41, s41, 0
	global_load_dword v58, v66, s[40:41]
	s_add_u32 s40, s40, s5
	s_addc_u32 s41, s41, 0
	global_load_dword v59, v66, s[40:41]
	s_add_u32 s40, s40, s5
	s_addc_u32 s41, s41, 0
	global_load_dword v60, v66, s[40:41]
	s_add_u32 s40, s40, s5
	s_addc_u32 s41, s41, 0
	global_load_dword v61, v66, s[40:41]
	s_add_u32 s40, s40, s5
	s_addc_u32 s41, s41, 0
	global_load_dword v62, v66, s[40:41]
	s_add_u32 s40, s40, s5
	s_addc_u32 s41, s41, 0
	global_load_dword v63, v66, s[40:41]
	s_add_u32 s40, s40, s5
	s_addc_u32 s41, s41, 0
	global_load_dword v64, v66, s[40:41]
	s_add_u32 s40, s40, s5
	s_addc_u32 s41, s41, 0
	global_load_dword v65, v66, s[40:41]
	s_mul_i32 s4, s39, s38
	s_add_u32 s4, s4, s33
	s_lshl_b32 s4, s4, 1
	s_add_u32 s44, s36, s4
	s_addc_u32 s45, s37, 0
	s_lshl_b32 s6, s38, 1
	v_mul_lo_u32 v78, v79, s6
	v_add_u32_e32 v78, v78, v92
	s_lshl_b32 s46, s38, 4
	s_waitcnt vmcnt(63)
	ds_write_b32 v76, v2 offset:0
	s_waitcnt vmcnt(62)
	ds_write_b32 v76, v3 offset:260
	s_waitcnt vmcnt(61)
	ds_write_b32 v76, v4 offset:520
	s_waitcnt vmcnt(60)
	ds_write_b32 v76, v5 offset:780
	s_waitcnt vmcnt(59)
	ds_write_b32 v76, v6 offset:1040
	s_waitcnt vmcnt(58)
	ds_write_b32 v76, v7 offset:1300
	s_waitcnt vmcnt(57)
	ds_write_b32 v76, v8 offset:1560
	s_waitcnt vmcnt(56)
	ds_write_b32 v76, v9 offset:1820
	s_waitcnt vmcnt(55)
	ds_write_b32 v76, v10 offset:2080
	s_waitcnt vmcnt(54)
	ds_write_b32 v76, v11 offset:2340
	s_waitcnt vmcnt(53)
	ds_write_b32 v76, v12 offset:2600
	s_waitcnt vmcnt(52)
	ds_write_b32 v76, v13 offset:2860
	s_waitcnt vmcnt(51)
	ds_write_b32 v76, v14 offset:3120
	s_waitcnt vmcnt(50)
	ds_write_b32 v76, v15 offset:3380
	s_waitcnt vmcnt(49)
	ds_write_b32 v76, v16 offset:3640
	s_waitcnt vmcnt(48)
	ds_write_b32 v76, v17 offset:3900
	s_waitcnt vmcnt(47)
	ds_write_b32 v76, v18 offset:4160
	s_waitcnt vmcnt(46)
	ds_write_b32 v76, v19 offset:4420
	s_waitcnt vmcnt(45)
	ds_write_b32 v76, v20 offset:4680
	s_waitcnt vmcnt(44)
	ds_write_b32 v76, v21 offset:4940
	s_waitcnt vmcnt(43)
	ds_write_b32 v76, v22 offset:5200
	s_waitcnt vmcnt(42)
	ds_write_b32 v76, v23 offset:5460
	s_waitcnt vmcnt(41)
	ds_write_b32 v76, v24 offset:5720
	s_waitcnt vmcnt(40)
	ds_write_b32 v76, v25 offset:5980
	s_waitcnt vmcnt(39)
	ds_write_b32 v76, v26 offset:6240
	s_waitcnt vmcnt(38)
	ds_write_b32 v76, v27 offset:6500
	s_waitcnt vmcnt(37)
	ds_write_b32 v76, v28 offset:6760
	s_waitcnt vmcnt(36)
	ds_write_b32 v76, v29 offset:7020
	s_waitcnt vmcnt(35)
	ds_write_b32 v76, v30 offset:7280
	s_waitcnt vmcnt(34)
	ds_write_b32 v76, v31 offset:7540
	s_waitcnt vmcnt(33)
	ds_write_b32 v76, v32 offset:7800
	s_waitcnt vmcnt(32)
	ds_write_b32 v76, v33 offset:8060
	s_waitcnt vmcnt(31)
	ds_write_b32 v76, v34 offset:8320
	s_waitcnt vmcnt(30)
	ds_write_b32 v76, v35 offset:8580
	s_waitcnt vmcnt(29)
	ds_write_b32 v76, v36 offset:8840
	s_waitcnt vmcnt(28)
	ds_write_b32 v76, v37 offset:9100
	s_waitcnt vmcnt(27)
	ds_write_b32 v76, v38 offset:9360
	s_waitcnt vmcnt(26)
	ds_write_b32 v76, v39 offset:9620
	s_waitcnt vmcnt(25)
	ds_write_b32 v76, v40 offset:9880
	s_waitcnt vmcnt(24)
	ds_write_b32 v76, v41 offset:10140
	s_waitcnt vmcnt(23)
; #define LAS __attribute__((address_space(3)))
; __device__ __forceinline__ unsigned cvtpk(float lo, float hi) { f32x2 v = {lo, hi}; bf16x2_t b = __builtin_convertvector(v, bf16x2_t); return __builtin_bit_cast(unsigned, b); }
; __device__ __forceinline__ void p0_item(const float* W, int ldw, int col0, int k0, const float* gain, bf16_t* WT, int K, int drow0, LAS float* scr, int lane) {
;     ...
;     for (int i = 0; i < 64; ++i) scr[i * 65 + lane] = v[i];
;     asm volatile("s_waitcnt lgkmcnt(0)" ::: "memory");
; #pragma unroll
;     for (int j = 0; j < 8; ++j) { const int n = (lane >> 3) + 8 * j; const LAS float* s = scr + (8 * c) * 65 + n;
;         u32x4 o; o.x = cvtpk(s[0 * 65] * g0[0], s[1 * 65] * g0[1]); o.y = cvtpk(s[2 * 65] * g0[2], s[3 * 65] * g0[3]); o.z = cvtpk(s[4 * 65] * g1[0], s[5 * 65] * g1[1]); o.w = cvtpk(s[6 * 65] * g1[2], s[7 * 65] * g1[3]);
;         *(u32x4*)(WT + (size_t)(drow0 + n) * K + k0 + 8 * c) = o; }
;     asm volatile("s_waitcnt lgkmcnt(0)" ::: "memory");
	ds_write_b32 v76, v42 offset:10400
	s_waitcnt vmcnt(22)
	ds_write_b32 v76, v43 offset:10660
	s_waitcnt vmcnt(21)
	ds_write_b32 v76, v44 offset:10920
	s_waitcnt vmcnt(20)
	ds_write_b32 v76, v45 offset:11180
	s_waitcnt vmcnt(19)
	ds_write_b32 v76, v46 offset:11440
	s_waitcnt vmcnt(18)
	ds_write_b32 v76, v47 offset:11700
	s_waitcnt vmcnt(17)
	ds_write_b32 v76, v48 offset:11960
	s_waitcnt vmcnt(16)
	ds_write_b32 v76, v49 offset:12220
	s_waitcnt vmcnt(15)
	ds_write_b32 v76, v50 offset:12480
	s_waitcnt vmcnt(14)
	ds_write_b32 v76, v51 offset:12740
	s_waitcnt vmcnt(13)
	ds_write_b32 v76, v52 offset:13000
	s_waitcnt vmcnt(12)
	ds_write_b32 v76, v53 offset:13260
	s_waitcnt vmcnt(11)
	ds_write_b32 v76, v54 offset:13520
	s_waitcnt vmcnt(10)
	ds_write_b32 v76, v55 offset:13780
	s_waitcnt vmcnt(9)
	ds_write_b32 v76, v56 offset:14040
	s_waitcnt vmcnt(8)
	ds_write_b32 v76, v57 offset:14300
	s_waitcnt vmcnt(7)
	ds_write_b32 v76, v58 offset:14560
	s_waitcnt vmcnt(6)
	ds_write_b32 v76, v59 offset:14820
	s_waitcnt vmcnt(5)
	ds_write_b32 v76, v60 offset:15080
	s_waitcnt vmcnt(4)
	ds_write_b32 v76, v61 offset:15340
	s_waitcnt vmcnt(3)
	ds_write_b32 v76, v62 offset:15600
	s_waitcnt vmcnt(2)
	ds_write_b32 v76, v63 offset:15860
	s_waitcnt vmcnt(1)
	ds_write_b32 v76, v64 offset:16120
	s_waitcnt vmcnt(0)
	ds_write_b32 v76, v65 offset:16380
	s_waitcnt lgkmcnt(0)
	ds_read_b32 v80, v77 offset:0
	ds_read_b32 v81, v77 offset:260
	ds_read_b32 v82, v77 offset:520
	ds_read_b32 v83, v77 offset:780
	ds_read_b32 v84, v77 offset:1040
	ds_read_b32 v85, v77 offset:1300
	ds_read_b32 v86, v77 offset:1560
	ds_read_b32 v87, v77 offset:1820
	s_waitcnt lgkmcnt(0)
	v_pk_mul_f32 v[84:85], v[84:85], v[72:73]
	v_pk_mul_f32 v[86:87], v[86:87], v[74:75]
	v_pk_mul_f32 v[80:81], v[80:81], v[68:69]
	v_pk_mul_f32 v[82:83], v[82:83], v[70:71]
	v_cvt_pk_bf16_f32 v90, v84, v85
	v_cvt_pk_bf16_f32 v91, v86, v87
	v_cvt_pk_bf16_f32 v88, v80, v81
	v_cvt_pk_bf16_f32 v89, v82, v83
	ds_read_b32 v80, v77 offset:32
	ds_read_b32 v81, v77 offset:292
	ds_read_b32 v82, v77 offset:552
	ds_read_b32 v83, v77 offset:812
	ds_read_b32 v84, v77 offset:1072
	ds_read_b32 v85, v77 offset:1332
	ds_read_b32 v86, v77 offset:1592
	ds_read_b32 v87, v77 offset:1852
	global_store_dwordx4 v78, v[88:91], s[44:45]
	s_add_u32 s44, s44, s46
	s_addc_u32 s45, s45, 0
	s_waitcnt lgkmcnt(0)
	v_pk_mul_f32 v[84:85], v[84:85], v[72:73]
	v_pk_mul_f32 v[86:87], v[86:87], v[74:75]
	v_pk_mul_f32 v[80:81], v[80:81], v[68:69]
	v_pk_mul_f32 v[82:83], v[82:83], v[70:71]
	v_cvt_pk_bf16_f32 v90, v84, v85
	v_cvt_pk_bf16_f32 v91, v86, v87
	v_cvt_pk_bf16_f32 v88, v80, v81
	v_cvt_pk_bf16_f32 v89, v82, v83
	ds_read_b32 v80, v77 offset:64
	ds_read_b32 v81, v77 offset:324
	ds_read_b32 v82, v77 offset:584
	ds_read_b32 v83, v77 offset:844
	ds_read_b32 v84, v77 offset:1104
	ds_read_b32 v85, v77 offset:1364
	ds_read_b32 v86, v77 offset:1624
	ds_read_b32 v87, v77 offset:1884
	global_store_dwordx4 v78, v[88:91], s[44:45]
	s_add_u32 s44, s44, s46
	s_addc_u32 s45, s45, 0
	s_waitcnt lgkmcnt(0)
	v_pk_mul_f32 v[84:85], v[84:85], v[72:73]
	v_pk_mul_f32 v[86:87], v[86:87], v[74:75]
	v_pk_mul_f32 v[80:81], v[80:81], v[68:69]
	v_pk_mul_f32 v[82:83], v[82:83], v[70:71]
	v_cvt_pk_bf16_f32 v90, v84, v85
	v_cvt_pk_bf16_f32 v91, v86, v87
	v_cvt_pk_bf16_f32 v88, v80, v81
	v_cvt_pk_bf16_f32 v89, v82, v83
	ds_read_b32 v80, v77 offset:96
	ds_read_b32 v81, v77 offset:356
	ds_read_b32 v82, v77 offset:616
	ds_read_b32 v83, v77 offset:876
	ds_read_b32 v84, v77 offset:1136
	ds_read_b32 v85, v77 offset:1396
	ds_read_b32 v86, v77 offset:1656
	ds_read_b32 v87, v77 offset:1916
	global_store_dwordx4 v78, v[88:91], s[44:45]
	s_add_u32 s44, s44, s46
	s_addc_u32 s45, s45, 0
	s_waitcnt lgkmcnt(0)
	v_pk_mul_f32 v[84:85], v[84:85], v[72:73]
	v_pk_mul_f32 v[86:87], v[86:87], v[74:75]
	v_pk_mul_f32 v[80:81], v[80:81], v[68:69]
	v_pk_mul_f32 v[82:83], v[82:83], v[70:71]
	v_cvt_pk_bf16_f32 v90, v84, v85
	v_cvt_pk_bf16_f32 v91, v86, v87
	v_cvt_pk_bf16_f32 v88, v80, v81
	v_cvt_pk_bf16_f32 v89, v82, v83
	ds_read_b32 v80, v77 offset:128
	ds_read_b32 v81, v77 offset:388
	ds_read_b32 v82, v77 offset:648
	ds_read_b32 v83, v77 offset:908
	ds_read_b32 v84, v77 offset:1168
	ds_read_b32 v85, v77 offset:1428
	ds_read_b32 v86, v77 offset:1688
	ds_read_b32 v87, v77 offset:1948
	global_store_dwordx4 v78, v[88:91], s[44:45]
	s_add_u32 s44, s44, s46
	s_addc_u32 s45, s45, 0
	s_waitcnt lgkmcnt(0)
	v_pk_mul_f32 v[84:85], v[84:85], v[72:73]
	v_pk_mul_f32 v[86:87], v[86:87], v[74:75]
	v_pk_mul_f32 v[80:81], v[80:81], v[68:69]
	v_pk_mul_f32 v[82:83], v[82:83], v[70:71]
	v_cvt_pk_bf16_f32 v90, v84, v85
	v_cvt_pk_bf16_f32 v91, v86, v87
	v_cvt_pk_bf16_f32 v88, v80, v81
	v_cvt_pk_bf16_f32 v89, v82, v83
	ds_read_b32 v80, v77 offset:160
	ds_read_b32 v81, v77 offset:420
	ds_read_b32 v82, v77 offset:680
	ds_read_b32 v83, v77 offset:940
	ds_read_b32 v84, v77 offset:1200
	ds_read_b32 v85, v77 offset:1460
	ds_read_b32 v86, v77 offset:1720
	ds_read_b32 v87, v77 offset:1980
	global_store_dwordx4 v78, v[88:91], s[44:45]
	s_add_u32 s44, s44, s46
	s_addc_u32 s45, s45, 0
	s_waitcnt lgkmcnt(0)
	v_pk_mul_f32 v[84:85], v[84:85], v[72:73]
	v_pk_mul_f32 v[86:87], v[86:87], v[74:75]
	v_pk_mul_f32 v[80:81], v[80:81], v[68:69]
	v_pk_mul_f32 v[82:83], v[82:83], v[70:71]
	v_cvt_pk_bf16_f32 v90, v84, v85
	v_cvt_pk_bf16_f32 v91, v86, v87
	v_cvt_pk_bf16_f32 v88, v80, v81
	v_cvt_pk_bf16_f32 v89, v82, v83
	ds_read_b32 v80, v77 offset:192
	ds_read_b32 v81, v77 offset:452
	ds_read_b32 v82, v77 offset:712
	ds_read_b32 v83, v77 offset:972
	ds_read_b32 v84, v77 offset:1232
	ds_read_b32 v85, v77 offset:1492
	ds_read_b32 v86, v77 offset:1752
	ds_read_b32 v87, v77 offset:2012
	global_store_dwordx4 v78, v[88:91], s[44:45]
	s_add_u32 s44, s44, s46
	s_addc_u32 s45, s45, 0
	s_waitcnt lgkmcnt(0)
	v_pk_mul_f32 v[84:85], v[84:85], v[72:73]
	v_pk_mul_f32 v[86:87], v[86:87], v[74:75]
	v_pk_mul_f32 v[80:81], v[80:81], v[68:69]
	v_pk_mul_f32 v[82:83], v[82:83], v[70:71]
	v_cvt_pk_bf16_f32 v90, v84, v85
	v_cvt_pk_bf16_f32 v91, v86, v87
	v_cvt_pk_bf16_f32 v88, v80, v81
	v_cvt_pk_bf16_f32 v89, v82, v83
	ds_read_b32 v80, v77 offset:224
	ds_read_b32 v81, v77 offset:484
	ds_read_b32 v82, v77 offset:744
	ds_read_b32 v83, v77 offset:1004
	ds_read_b32 v84, v77 offset:1264
	ds_read_b32 v85, v77 offset:1524
	ds_read_b32 v86, v77 offset:1784
	ds_read_b32 v87, v77 offset:2044
	global_store_dwordx4 v78, v[88:91], s[44:45]
	s_add_u32 s44, s44, s46
	s_addc_u32 s45, s45, 0
	s_waitcnt lgkmcnt(0)
	v_pk_mul_f32 v[84:85], v[84:85], v[72:73]
	v_pk_mul_f32 v[86:87], v[86:87], v[74:75]
	v_pk_mul_f32 v[80:81], v[80:81], v[68:69]
	v_pk_mul_f32 v[82:83], v[82:83], v[70:71]
	v_cvt_pk_bf16_f32 v90, v84, v85
	v_cvt_pk_bf16_f32 v91, v86, v87
	v_cvt_pk_bf16_f32 v88, v80, v81
	v_cvt_pk_bf16_f32 v89, v82, v83
	global_store_dwordx4 v78, v[88:91], s[44:45]
	s_add_i32 s55, s55, s1
	s_cmpk_gt_i32 s55, 0x567f
	s_cbranch_scc0 .Lp0_loop
